# attention main loop: QK^T K-fragment LDS reads issued two steps ahead (second fragment buffer)
# baseline (speedup 1.0000x reference)
.LBB0_453:
	ds_read_b128 v[66:69], v209 offset:49152
	ds_read_b128 v[70:73], v209 offset:57344
	ds_read_b128 v[232:235], v214 offset:49152
	ds_read_b128 v[236:239], v214 offset:57344
	ds_read_b128 v[200:203], v213 offset:49152
	ds_read_b128 v[204:207], v213 offset:57344
	v_add_f32_e32 v164, 0, v165
	v_add_f32_e32 v164, v179, v164
	s_waitcnt lgkmcnt(5)
	v_mfma_f32_32x32x16_bf16 v[82:97], v[66:69], v[120:123], 0
	v_add_f32_e32 v164, v166, v164
	v_add_f32_e32 v164, v221, v164
	v_add_f32_e32 v164, v178, v164
	v_add_f32_e32 v164, v231, v164
	v_add_f32_e32 v164, v167, v164
	v_add_f32_e32 v164, v177, v164
	v_add_f32_e32 v164, v173, v164
	s_waitcnt lgkmcnt(4)
	v_mfma_f32_32x32x16_bf16 v[66:81], v[70:73], v[120:123], 0
	v_add_f32_e32 v164, v175, v164
	v_add_f32_e32 v164, v174, v164
	v_add_f32_e32 v164, v176, v164
	v_exp_f32_e32 v162, v162
	v_add_f32_e32 v164, v169, v164
	v_exp_f32_e32 v163, v163
	v_add_f32_e32 v164, v171, v164
	s_waitcnt lgkmcnt(3)
	v_mfma_f32_32x32x16_bf16 v[82:97], v[232:235], v[112:115], v[82:97]
	v_exp_f32_e32 v160, v160
	v_add_f32_e32 v164, v170, v164
	v_exp_f32_e32 v161, v161
	v_add_f32_e32 v164, v172, v164
	v_exp_f32_e32 v156, v156
	v_add_f32_e32 v164, v162, v164
	v_exp_f32_e32 v157, v157
	s_waitcnt lgkmcnt(2)
	v_mfma_f32_32x32x16_bf16 v[66:81], v[236:239], v[112:115], v[66:81]
	ds_read_b128 v[232:235], v212 offset:49152
	ds_read_b128 v[236:239], v212 offset:57344
	v_add_f32_e32 v164, v163, v164
	v_exp_f32_e32 v152, v152
	v_add_f32_e32 v164, v160, v164
	v_exp_f32_e32 v153, v153
	v_add_f32_e32 v164, v161, v164
	v_exp_f32_e32 v150, v150
	s_waitcnt lgkmcnt(3)
	v_mfma_f32_32x32x16_bf16 v[82:97], v[200:203], v[128:131], v[82:97]
	v_add_f32_e32 v164, v156, v164
	v_exp_f32_e32 v151, v151
	v_add_f32_e32 v164, v157, v164
	v_exp_f32_e32 v158, v158
	v_add_f32_e32 v164, v152, v164
	v_exp_f32_e32 v159, v159
	v_add_f32_e32 v164, v153, v164
	s_waitcnt lgkmcnt(2)
	v_mfma_f32_32x32x16_bf16 v[66:81], v[204:207], v[128:131], v[66:81]
	ds_read_b128 v[200:203], v211 offset:49152
	ds_read_b128 v[204:207], v211 offset:57344
	v_exp_f32_e32 v154, v154
	v_add_f32_e32 v164, v150, v164
	v_exp_f32_e32 v155, v155
	v_add_f32_e32 v164, v151, v164
	v_exp_f32_e32 v148, v148
	v_add_f32_e32 v164, v158, v164
	s_waitcnt lgkmcnt(3)
	v_mfma_f32_32x32x16_bf16 v[82:97], v[232:235], v[124:127], v[82:97]
	v_exp_f32_e32 v149, v149
	v_add_f32_e32 v164, v159, v164
	v_add_f32_e32 v164, v154, v164
	v_add_f32_e32 v164, v155, v164
	v_add_f32_e32 v164, v148, v164
	v_add_f32_e32 v218, v149, v164
	v_mov_b32_e32 v219, v218
	s_waitcnt lgkmcnt(2)
	v_mfma_f32_32x32x16_bf16 v[66:81], v[236:239], v[124:127], v[66:81]
	ds_read_b128 v[232:235], v210 offset:49152
	ds_read_b128 v[236:239], v210 offset:57344
	v_permlane32_swap_b32_e32 v218, v219
	s_waitcnt lgkmcnt(3)
	v_mfma_f32_32x32x16_bf16 v[82:97], v[200:203], v[116:119], v[82:97]
	s_waitcnt lgkmcnt(2)
	v_mfma_f32_32x32x16_bf16 v[66:81], v[204:207], v[116:119], v[66:81]
	ds_read_b128 v[200:203], v216 offset:49152
	ds_read_b128 v[204:207], v216 offset:57344
	s_waitcnt lgkmcnt(3)
	v_mfma_f32_32x32x16_bf16 v[82:97], v[232:235], v[108:111], v[82:97]
	s_waitcnt lgkmcnt(2)
	v_mfma_f32_32x32x16_bf16 v[66:81], v[236:239], v[108:111], v[66:81]
	ds_read_b128 v[232:235], v215 offset:49152
	ds_read_b128 v[236:239], v215 offset:57344
	s_waitcnt lgkmcnt(3)
	v_mfma_f32_32x32x16_bf16 v[82:97], v[200:203], v[104:107], v[82:97]
	s_waitcnt lgkmcnt(2)
	v_mfma_f32_32x32x16_bf16 v[66:81], v[204:207], v[104:107], v[66:81]
	v_cvt_pk_bf16_f32 v164, v165, v179
	v_cvt_pk_bf16_f32 v165, v166, v221
	v_cvt_pk_bf16_f32 v166, v178, v231
	v_cvt_pk_bf16_f32 v167, v167, v177
	v_cvt_pk_bf16_f32 v220, v173, v175
	v_cvt_pk_bf16_f32 v221, v174, v176
	s_waitcnt lgkmcnt(1)
	v_mfma_f32_32x32x16_bf16 v[82:97], v[232:235], v[100:103], v[82:97]
	v_cvt_pk_bf16_f32 v222, v169, v171
	v_permlane32_swap_b32_e32 v164, v166
	v_cvt_pk_bf16_f32 v223, v170, v172
	v_permlane32_swap_b32_e32 v220, v222
	v_cvt_pk_bf16_f32 v170, v162, v163
	s_waitcnt lgkmcnt(0)
	v_mfma_f32_32x32x16_bf16 v[66:81], v[236:239], v[100:103], v[66:81]
	v_cvt_pk_bf16_f32 v171, v160, v161
	v_cvt_pk_bf16_f32 v172, v156, v157
	v_cvt_pk_bf16_f32 v173, v152, v153
	v_cvt_pk_bf16_f32 v174, v150, v151
	v_cvt_pk_bf16_f32 v175, v158, v159
	v_cvt_pk_bf16_f32 v176, v154, v155
	v_cvt_pk_bf16_f32 v177, v148, v149
	v_permlane32_swap_b32_e32 v165, v167
	v_permlane32_swap_b32_e32 v221, v223
	v_permlane32_swap_b32_e32 v170, v172
	v_permlane32_swap_b32_e32 v171, v173
	v_permlane32_swap_b32_e32 v174, v176
	v_permlane32_swap_b32_e32 v175, v177
	v_add_co_u32_e32 v148, vcc, s1, v180
	s_nop 1
	v_addc_co_u32_e32 v149, vcc, -1, v181, vcc
	v_add_co_u32_e32 v152, vcc, s28, v180
	s_nop 1
	v_addc_co_u32_e32 v153, vcc, -1, v181, vcc
	v_add_co_u32_e32 v156, vcc, s19, v180
	global_load_dwordx4 v[148:151], v[148:149], off
	s_nop 0
	global_load_dwordx4 v[152:155], v[152:153], off
	v_addc_co_u32_e32 v157, vcc, -1, v181, vcc
	v_add_co_u32_e32 v160, vcc, s27, v180
	s_nop 1
	v_addc_co_u32_e32 v161, vcc, -1, v181, vcc
	global_load_dwordx4 v[156:159], v[156:157], off
	s_nop 0
	global_load_dwordx4 v[160:163], v[160:161], off
	ds_read_b64_tr_b16 v[232:233], v192 offset:0
	ds_read_b64_tr_b16 v[234:235], v192 offset:0x800
	ds_read_b64_tr_b16 v[236:237], v192 offset:0x1000
	ds_read_b64_tr_b16 v[238:239], v192 offset:0x1800
	ds_read_b64_tr_b16 v[240:241], v192 offset:0x2000
	ds_read_b64_tr_b16 v[242:243], v192 offset:0x2800
	ds_read_b64_tr_b16 v[244:245], v192 offset:0x3000
	ds_read_b64_tr_b16 v[246:247], v192 offset:0x3800
	s_waitcnt lgkmcnt(0)
	s_nop 0
	v_mfma_f32_32x32x16_bf16 v[2:17], v[164:167], v[232:235], v[2:17]
	ds_read_b64_tr_b16 v[232:233], v192 offset:0x200
	ds_read_b64_tr_b16 v[234:235], v192 offset:0xa00
	v_mfma_f32_32x32x16_bf16 v[2:17], v[220:223], v[236:239], v[2:17]
	ds_read_b64_tr_b16 v[236:237], v192 offset:0x1200
	ds_read_b64_tr_b16 v[238:239], v192 offset:0x1a00
	v_mfma_f32_32x32x16_bf16 v[2:17], v[170:173], v[240:243], v[2:17]
	ds_read_b64_tr_b16 v[240:241], v192 offset:0x2200
	ds_read_b64_tr_b16 v[242:243], v192 offset:0x2a00
	v_mfma_f32_32x32x16_bf16 v[2:17], v[174:177], v[244:247], v[2:17]
	ds_read_b64_tr_b16 v[244:245], v192 offset:0x3200
	ds_read_b64_tr_b16 v[246:247], v192 offset:0x3a00
	s_waitcnt lgkmcnt(0)
	v_mfma_f32_32x32x16_bf16 v[50:65], v[164:167], v[232:235], v[50:65]
	ds_read_b64_tr_b16 v[232:233], v192 offset:0x400
	ds_read_b64_tr_b16 v[234:235], v192 offset:0xc00
	v_mfma_f32_32x32x16_bf16 v[50:65], v[220:223], v[236:239], v[50:65]
	ds_read_b64_tr_b16 v[236:237], v192 offset:0x1400
	ds_read_b64_tr_b16 v[238:239], v192 offset:0x1c00
	v_mfma_f32_32x32x16_bf16 v[50:65], v[170:173], v[240:243], v[50:65]
	ds_read_b64_tr_b16 v[240:241], v192 offset:0x2400
	ds_read_b64_tr_b16 v[242:243], v192 offset:0x2c00
	v_mfma_f32_32x32x16_bf16 v[50:65], v[174:177], v[244:247], v[50:65]
	ds_read_b64_tr_b16 v[244:245], v192 offset:0x3400
	ds_read_b64_tr_b16 v[246:247], v192 offset:0x3c00
	s_waitcnt lgkmcnt(0)
	v_mfma_f32_32x32x16_bf16 v[34:49], v[164:167], v[232:235], v[34:49]
	ds_read_b64_tr_b16 v[232:233], v192 offset:0x600
	ds_read_b64_tr_b16 v[234:235], v192 offset:0xe00
	v_mfma_f32_32x32x16_bf16 v[34:49], v[220:223], v[236:239], v[34:49]
	ds_read_b64_tr_b16 v[236:237], v192 offset:0x1600
	ds_read_b64_tr_b16 v[238:239], v192 offset:0x1e00
	v_mfma_f32_32x32x16_bf16 v[34:49], v[170:173], v[240:243], v[34:49]
	ds_read_b64_tr_b16 v[240:241], v192 offset:0x2600
	ds_read_b64_tr_b16 v[242:243], v192 offset:0x2e00
	v_mfma_f32_32x32x16_bf16 v[34:49], v[174:177], v[244:247], v[34:49]
	ds_read_b64_tr_b16 v[244:245], v192 offset:0x3600
	ds_read_b64_tr_b16 v[246:247], v192 offset:0x3e00
	s_waitcnt lgkmcnt(0)
	v_mfma_f32_32x32x16_bf16 v[18:33], v[164:167], v[232:235], v[18:33]
	v_max_f32_e32 v164, v83, v83
	v_max_f32_e32 v165, v82, v82
	v_max_f32_e32 v164, v165, v164
	v_max3_f32 v164, v164, v84, v85
	v_max3_f32 v164, v164, v86, v87
	v_max3_f32 v164, v164, v88, v89
	v_max3_f32 v164, v164, v90, v91
	v_max3_f32 v164, v164, v92, v93
	v_max3_f32 v164, v164, v94, v95
	v_mfma_f32_32x32x16_bf16 v[18:33], v[220:223], v[236:239], v[18:33]
	v_max3_f32 v164, v164, v96, v97
	v_max3_f32 v164, v164, v66, v67
	v_max3_f32 v164, v164, v68, v69
	v_max3_f32 v164, v164, v70, v71
	v_max3_f32 v164, v164, v72, v73
	v_max3_f32 v164, v164, v74, v75
	v_max3_f32 v164, v164, v76, v77
	v_max3_f32 v164, v164, v78, v79
	v_mfma_f32_32x32x16_bf16 v[18:33], v[170:173], v[240:243], v[18:33]
	v_max3_f32 v164, v164, v80, v81
	v_mov_b32_e32 v165, v164
	s_nop 1
	v_permlane32_swap_b32_e32 v164, v165
	v_max_f32_e32 v165, v165, v165
	v_max_f32_e32 v164, v164, v164
	v_max_f32_e32 v164, v164, v165
	v_sub_f32_e32 v165, v164, v168
	v_cmp_ge_f32_e32 vcc, s0, v165
	v_max_f32_e32 v165, v168, v168
	v_max_f32_e32 v164, v165, v164
	v_mfma_f32_32x32x16_bf16 v[18:33], v[174:177], v[244:247], v[18:33]
	v_sub_f32_e32 v165, v168, v164
	v_mul_f32_e32 v165, 0x3e0293ee, v165
	v_exp_f32_e32 v165, v165
	s_cmp_eq_u64 vcc, exec
	s_cselect_b64 s[42:43], -1, 0
	s_barrier
	s_waitcnt vmcnt(4)
	v_cndmask_b32_e64 v220, v165, 1.0, s[42:43]
	v_cmp_gt_f32_e32 vcc, 1.0, v220
	s_waitcnt vmcnt(7)
	ds_write_b128 v195, v[132:135]
	s_waitcnt vmcnt(6)
	ds_write_b128 v208, v[140:143]
	s_waitcnt vmcnt(5)
	ds_write_b128 v193, v[136:139] offset:32768
	s_waitcnt vmcnt(4)
	ds_write_b128 v194, v[144:147] offset:32768
	s_cbranch_vccz .LBB0_457
	s_and_saveexec_b64 s[4:5], s[40:41]
	ds_write_b32 v189, v220 offset:128
	s_or_b64 exec, exec, s[4:5]
	s_waitcnt lgkmcnt(0)
	v_add_u32_e32 v165, v188, v98
	ds_read_b128 v[170:173], v165 offset:224
	ds_read_b128 v[174:177], v165 offset:192
	ds_read_b128 v[232:235], v165 offset:160
	ds_read_b128 v[236:239], v165 offset:128
	s_waitcnt lgkmcnt(3)
	v_pk_mul_f32 v[14:15], v[14:15], v[170:171]
	s_waitcnt lgkmcnt(2)
	v_pk_mul_f32 v[10:11], v[10:11], v[174:175]
	s_waitcnt lgkmcnt(1)
	v_pk_mul_f32 v[6:7], v[6:7], v[232:233]
	v_pk_mul_f32 v[16:17], v[16:17], v[172:173]
	v_pk_mul_f32 v[12:13], v[12:13], v[176:177]
	v_pk_mul_f32 v[8:9], v[8:9], v[234:235]
	s_waitcnt lgkmcnt(0)
	v_pk_mul_f32 v[4:5], v[4:5], v[238:239]
	v_pk_mul_f32 v[2:3], v[2:3], v[236:237]
	v_pk_mul_f32 v[62:63], v[62:63], v[170:171]
	v_pk_mul_f32 v[58:59], v[58:59], v[174:175]
	v_pk_mul_f32 v[54:55], v[54:55], v[232:233]
	v_pk_mul_f32 v[64:65], v[64:65], v[172:173]
	v_pk_mul_f32 v[60:61], v[60:61], v[176:177]
	v_pk_mul_f32 v[56:57], v[56:57], v[234:235]
	v_pk_mul_f32 v[52:53], v[52:53], v[238:239]
	v_pk_mul_f32 v[50:51], v[50:51], v[236:237]
	v_pk_mul_f32 v[46:47], v[46:47], v[170:171]
	v_pk_mul_f32 v[42:43], v[42:43], v[174:175]
	v_pk_mul_f32 v[38:39], v[38:39], v[232:233]
	v_pk_mul_f32 v[48:49], v[48:49], v[172:173]
	v_pk_mul_f32 v[44:45], v[44:45], v[176:177]
	v_pk_mul_f32 v[40:41], v[40:41], v[234:235]
	v_pk_mul_f32 v[36:37], v[36:37], v[238:239]
	v_pk_mul_f32 v[34:35], v[34:35], v[236:237]
	v_pk_mul_f32 v[30:31], v[30:31], v[170:171]
	v_pk_mul_f32 v[26:27], v[26:27], v[174:175]
	v_pk_mul_f32 v[22:23], v[22:23], v[232:233]
	v_pk_mul_f32 v[32:33], v[32:33], v[172:173]
	v_pk_mul_f32 v[28:29], v[28:29], v[176:177]
	v_pk_mul_f32 v[24:25], v[24:25], v[234:235]
	v_pk_mul_f32 v[20:21], v[20:21], v[238:239]
	v_pk_mul_f32 v[18:19], v[18:19], v[236:237]
.LBB0_457:
	v_cndmask_b32_e64 v221, v164, v168, s[42:43]
	v_mul_f32_e32 v222, 0xbe0293ee, v221
	v_fmamk_f32 v82, v82, 0x3e0293ee, v222
	v_fmamk_f32 v83, v83, 0x3e0293ee, v222
	v_fmamk_f32 v84, v84, 0x3e0293ee, v222
	v_fmamk_f32 v85, v85, 0x3e0293ee, v222
	v_fmamk_f32 v86, v86, 0x3e0293ee, v222
	v_fmamk_f32 v87, v87, 0x3e0293ee, v222
	v_fmamk_f32 v88, v88, 0x3e0293ee, v222
	v_fmamk_f32 v89, v89, 0x3e0293ee, v222
	v_fmamk_f32 v90, v90, 0x3e0293ee, v222
	v_fmamk_f32 v91, v91, 0x3e0293ee, v222
	v_fmamk_f32 v92, v92, 0x3e0293ee, v222
	v_fmamk_f32 v93, v93, 0x3e0293ee, v222
	v_fmamk_f32 v94, v94, 0x3e0293ee, v222
	v_fmamk_f32 v95, v95, 0x3e0293ee, v222
	v_fmamk_f32 v96, v96, 0x3e0293ee, v222
	v_fmamk_f32 v97, v97, 0x3e0293ee, v222
	v_exp_f32_e32 v164, v82
	v_exp_f32_e32 v179, v83
	v_exp_f32_e32 v165, v84
	v_exp_f32_e32 v178, v85
	v_exp_f32_e32 v166, v86
	v_exp_f32_e32 v177, v87
	v_exp_f32_e32 v167, v88
	v_exp_f32_e32 v176, v89
	v_exp_f32_e32 v168, v90
	v_exp_f32_e32 v175, v91
	v_exp_f32_e32 v169, v92
	v_exp_f32_e32 v174, v93
	v_exp_f32_e32 v170, v94
	v_exp_f32_e32 v173, v95
	v_exp_f32_e32 v171, v96
	v_exp_f32_e32 v172, v97
	v_fmamk_f32 v238, v66, 0x3e0293ee, v222
	v_fmamk_f32 v239, v67, 0x3e0293ee, v222
	v_fmamk_f32 v240, v68, 0x3e0293ee, v222
	v_fmamk_f32 v241, v69, 0x3e0293ee, v222
	v_fmamk_f32 v242, v70, 0x3e0293ee, v222
	v_fmamk_f32 v231, v71, 0x3e0293ee, v222
	v_fmamk_f32 v232, v72, 0x3e0293ee, v222
	v_fmamk_f32 v233, v73, 0x3e0293ee, v222
	v_fmamk_f32 v234, v74, 0x3e0293ee, v222
	v_fmamk_f32 v235, v75, 0x3e0293ee, v222
	v_fmamk_f32 v236, v76, 0x3e0293ee, v222
	v_fmamk_f32 v237, v77, 0x3e0293ee, v222
	v_fmamk_f32 v223, v78, 0x3e0293ee, v222
	v_fmamk_f32 v243, v79, 0x3e0293ee, v222
	v_fmamk_f32 v244, v80, 0x3e0293ee, v222
	v_fmac_f32_e32 v222, 0x3e0293ee, v81
	s_waitcnt lgkmcnt(0)
	s_barrier
	ds_read_b128 v[66:69], v209 offset:32768
	ds_read_b128 v[70:73], v209 offset:40960
	ds_read_b128 v[246:249], v214 offset:32768
	ds_read_b128 v[196:199], v214 offset:40960
	ds_read_b128 v[200:203], v213 offset:32768
	ds_read_b128 v[204:207], v213 offset:40960
	v_exp_f32_e32 v231, v231
	v_exp_f32_e32 v232, v232
	s_waitcnt lgkmcnt(5)
	v_mfma_f32_32x32x16_bf16 v[82:97], v[66:69], v[120:123], 0
	v_exp_f32_e32 v233, v233
	v_exp_f32_e32 v234, v234
	v_exp_f32_e32 v235, v235
	v_exp_f32_e32 v236, v236
	v_exp_f32_e32 v237, v237
	s_waitcnt lgkmcnt(4)
	v_mfma_f32_32x32x16_bf16 v[66:81], v[70:73], v[120:123], 0
	s_waitcnt lgkmcnt(3)
	v_mfma_f32_32x32x16_bf16 v[82:97], v[246:249], v[112:115], v[82:97]
	s_waitcnt lgkmcnt(2)
	v_mfma_f32_32x32x16_bf16 v[66:81], v[196:199], v[112:115], v[66:81]
	ds_read_b128 v[196:199], v212 offset:32768
	ds_read_b128 v[246:249], v212 offset:40960
	s_waitcnt lgkmcnt(3)
	v_mfma_f32_32x32x16_bf16 v[82:97], v[200:203], v[128:131], v[82:97]
	s_waitcnt lgkmcnt(2)
	v_mfma_f32_32x32x16_bf16 v[66:81], v[204:207], v[128:131], v[66:81]
	ds_read_b128 v[200:203], v211 offset:32768
	ds_read_b128 v[204:207], v211 offset:40960
	s_waitcnt lgkmcnt(3)
	v_mfma_f32_32x32x16_bf16 v[82:97], v[196:199], v[124:127], v[82:97]
	s_waitcnt lgkmcnt(2)
	v_mfma_f32_32x32x16_bf16 v[66:81], v[246:249], v[124:127], v[66:81]
	ds_read_b128 v[196:199], v210 offset:32768
	ds_read_b128 v[246:249], v210 offset:40960
	s_waitcnt lgkmcnt(3)
	v_mfma_f32_32x32x16_bf16 v[82:97], v[200:203], v[116:119], v[82:97]
	s_waitcnt lgkmcnt(2)
	v_mfma_f32_32x32x16_bf16 v[66:81], v[204:207], v[116:119], v[66:81]
	ds_read_b128 v[200:203], v216 offset:32768
	ds_read_b128 v[204:207], v216 offset:40960
	s_waitcnt lgkmcnt(3)
	v_mfma_f32_32x32x16_bf16 v[82:97], v[196:199], v[108:111], v[82:97]
	s_waitcnt lgkmcnt(2)
	v_mfma_f32_32x32x16_bf16 v[66:81], v[246:249], v[108:111], v[66:81]
	ds_read_b128 v[196:199], v215 offset:32768
	ds_read_b128 v[246:249], v215 offset:40960
	s_waitcnt lgkmcnt(3)
	v_mfma_f32_32x32x16_bf16 v[82:97], v[200:203], v[104:107], v[82:97]
	s_waitcnt lgkmcnt(2)
	v_mfma_f32_32x32x16_bf16 v[66:81], v[204:207], v[104:107], v[66:81]
	s_waitcnt lgkmcnt(1)
	v_mfma_f32_32x32x16_bf16 v[82:97], v[196:199], v[100:103], v[82:97]
	v_exp_f32_e32 v196, v238
	v_exp_f32_e32 v238, v242
	v_exp_f32_e32 v242, v222
	v_add_f32_e32 v222, 0, v164
	v_add_f32_e32 v222, v179, v222
	v_add_f32_e32 v222, v165, v222
	v_add_f32_e32 v222, v178, v222
	v_add_f32_e32 v222, v166, v222
	v_add_f32_e32 v222, v177, v222
	v_add_f32_e32 v222, v167, v222
	v_add_f32_e32 v222, v176, v222
	v_add_f32_e32 v222, v168, v222
	v_add_f32_e32 v222, v175, v222
	v_add_f32_e32 v222, v169, v222
	v_add_f32_e32 v222, v174, v222
	v_add_f32_e32 v222, v170, v222
	v_exp_f32_e32 v197, v239
	v_add_f32_e32 v222, v173, v222
	v_exp_f32_e32 v198, v240
	v_add_f32_e32 v222, v171, v222
	v_exp_f32_e32 v199, v241
	v_add_f32_e32 v222, v172, v222
	v_add_f32_e32 v222, v196, v222
	v_add_f32_e32 v222, v197, v222
	v_add_f32_e32 v222, v198, v222
	v_add_f32_e32 v222, v199, v222
	v_add_f32_e32 v222, v238, v222
	v_add_f32_e32 v222, v231, v222
	v_add_f32_e32 v222, v232, v222
	v_add_f32_e32 v222, v233, v222
	v_exp_f32_e32 v239, v223
	v_add_f32_e32 v222, v234, v222
	v_exp_f32_e32 v240, v243
	v_add_f32_e32 v222, v235, v222
	s_waitcnt lgkmcnt(0)
	v_mfma_f32_32x32x16_bf16 v[66:81], v[246:249], v[100:103], v[66:81]
	v_exp_f32_e32 v241, v244
	v_add_f32_e32 v222, v236, v222
	v_add_f32_e32 v222, v237, v222
	v_add_f32_e32 v222, v239, v222
	v_add_f32_e32 v222, v240, v222
	v_add_f32_e32 v222, v241, v222
	v_add_f32_e32 v222, v242, v222
	v_mov_b32_e32 v223, v222
	v_cvt_pk_bf16_f32 v164, v164, v179
	v_cvt_pk_bf16_f32 v165, v165, v178
	v_cvt_pk_bf16_f32 v166, v166, v177
	v_cvt_pk_bf16_f32 v167, v167, v176
	v_cvt_pk_bf16_f32 v168, v168, v175
	v_cvt_pk_bf16_f32 v169, v169, v174
	v_cvt_pk_bf16_f32 v170, v170, v173
	v_cvt_pk_bf16_f32 v171, v171, v172
	v_cvt_pk_bf16_f32 v172, v196, v197
	v_cvt_pk_bf16_f32 v173, v198, v199
	v_cvt_pk_bf16_f32 v174, v238, v231
	v_cvt_pk_bf16_f32 v175, v232, v233
	v_cvt_pk_bf16_f32 v176, v234, v235
	v_cvt_pk_bf16_f32 v177, v236, v237
	v_cvt_pk_bf16_f32 v178, v239, v240
	v_cvt_pk_bf16_f32 v179, v241, v242
	s_nop 1
	v_permlane32_swap_b32_e32 v222, v223
	v_permlane32_swap_b32_e32 v164, v166
	v_permlane32_swap_b32_e32 v165, v167
	v_permlane32_swap_b32_e32 v168, v170
	v_permlane32_swap_b32_e32 v169, v171
	v_permlane32_swap_b32_e32 v172, v174
	v_permlane32_swap_b32_e32 v173, v175
	v_permlane32_swap_b32_e32 v176, v178
	v_permlane32_swap_b32_e32 v177, v179
	s_cmp_gt_u32 s6, 64
	s_cselect_b64 s[4:5], -1, 0
	s_and_b64 vcc, exec, s[4:5]
	s_cbranch_vccnz .LBB0_459
	v_add_co_u32_e32 v132, vcc, 0xffffc000, v180
	s_nop 1
	v_addc_co_u32_e32 v133, vcc, -1, v181, vcc
	v_add_co_u32_e32 v136, vcc, 0xff77c000, v180
	s_nop 1
	v_addc_co_u32_e32 v137, vcc, -1, v181, vcc
	v_add_co_u32_e32 v144, vcc, 0xff780000, v180
	global_load_dwordx4 v[132:135], v[132:133], off
	s_nop 0
	global_load_dwordx4 v[136:139], v[136:137], off
	v_addc_co_u32_e32 v145, vcc, -1, v181, vcc
	global_load_dwordx4 v[140:143], v[180:181], off
	s_nop 0
	global_load_dwordx4 v[144:147], v[144:145], off

.LBB0_471:
	v_mov_b64_e32 v[200:201], 0x100
	v_mov_b64_e32 v[202:203], 0xff
	v_mov_b64_e32 v[204:205], 0x80
	v_mov_b64_e32 v[206:207], 0x7f
	v_readlane_b32 s6, v253, 4
	s_mov_b64 s[4:5], s[96:97]
	v_mov_b32_e32 v10, v0
	v_readlane_b32 s7, v253, 5
	s_andn2_b64 vcc, exec, s[6:7]
	v_readfirstlane_b32 s10, v10
	s_cbranch_vccnz .LBB0_491
	v_lshlrev_b32_e32 v2, 4, v10
	v_add_u32_e32 v3, 0x2000, v2
	v_ashrrev_i32_e32 v4, 31, v3
	v_lshrrev_b32_e32 v4, 22, v4
	v_add_u32_e32 v4, v3, v4
	v_ashrrev_i32_e32 v4, 10, v4
	v_mul_i32_i24_e32 v5, 0x400, v4
	v_sub_u32_e32 v3, v3, v5
	v_lshrrev_b32_e32 v5, 4, v3
	v_bitop3_b32 v3, v5, v3, 32 bitop3:0x6c
	v_ashrrev_i32_e32 v5, 31, v3
	v_lshrrev_b32_e32 v5, 26, v5
	v_add_u32_e32 v5, v3, v5
	v_lshlrev_b32_e32 v7, 3, v4
	v_ashrrev_i32_e32 v6, 6, v5
	v_and_b32_e32 v7, -16, v7
	v_and_b32_e32 v5, 0xc0, v5
	v_add_u32_e32 v7, v6, v7
	v_sub_u32_e32 v3, v3, v5
	s_load_dwordx2 s[20:21], s[4:5], 0xb8
	v_and_b32_e32 v6, 3, v6
	s_mov_b32 s4, 0x7fffe0
	v_lshrrev_b32_e32 v8, 2, v7
	v_lshlrev_b32_e32 v9, 1, v7
	v_lshlrev_b32_e32 v4, 5, v4
	v_ashrrev_i16_sdwa v3, v226, sext(v3) dst_sel:DWORD dst_unused:UNUSED_PAD src0_sel:DWORD src1_sel:BYTE_0
	v_and_or_b32 v6, v7, s4, v6
	v_and_b32_e32 v8, 4, v8
	v_and_b32_e32 v9, 24, v9
	v_and_b32_e32 v4, 32, v4
	v_bfe_i32 v3, v3, 0, 16
	v_or3_b32 v6, v6, v8, v9
	v_add_lshl_u32 v3, v4, v3, 1
	v_lshl_add_u32 v132, v6, 9, v3
	v_lshl_add_u32 v134, v7, 9, v3
	v_bfe_i32 v3, v10, 27, 1
	v_lshrrev_b32_e32 v3, 22, v3
	v_add_u32_e32 v3, v2, v3
	v_and_b32_e32 v3, 0xfffffc00, v3
	v_sub_u32_e32 v2, v2, v3
	v_lshrrev_b32_e32 v3, 4, v2
	v_ashrrev_i32_e32 v5, 31, v10
	v_bitop3_b32 v2, v3, v2, 32 bitop3:0x6c
	v_lshrrev_b32_e32 v5, 26, v5
	v_ashrrev_i32_e32 v3, 31, v2
	v_add_u32_e32 v5, v10, v5
	s_waitcnt lgkmcnt(0)
	s_add_u32 s6, s20, 0x18100000
	v_lshrrev_b32_e32 v3, 26, v3
	v_ashrrev_i32_e32 v5, 6, v5
	s_addc_u32 s7, s21, 0
	v_add_u32_e32 v3, v2, v3
	v_lshlrev_b32_e32 v6, 3, v5
	s_add_u32 s8, s20, 0x31d24000
	v_ashrrev_i32_e32 v4, 6, v3
	v_and_b32_e32 v6, -16, v6
	v_and_b32_e32 v3, 0xc0, v3
	s_addc_u32 s9, s21, 0
	s_ashr_i32 s36, s10, 6
	v_add_u32_e32 v6, v4, v6
	v_and_b32_e32 v4, 3, v4
	v_sub_u32_e32 v2, v2, v3
	s_ashr_i32 s11, s10, 8
	s_lshl_b32 s52, s36, 10
	v_and_or_b32 v4, v6, s4, v4
	v_lshrrev_b32_e32 v7, 2, v6
	v_lshlrev_b32_e32 v8, 1, v6
	v_lshlrev_b32_e32 v5, 5, v5
	v_ashrrev_i16_sdwa v2, v226, sext(v2) dst_sel:DWORD dst_unused:UNUSED_PAD src0_sel:DWORD src1_sel:BYTE_0
	v_readlane_b32 s4, v254, 56
	v_and_b32_e32 v7, 4, v7
	v_and_b32_e32 v8, 24, v8
	v_and_b32_e32 v5, 32, v5
	v_bfe_i32 v2, v2, 0, 16
	v_readlane_b32 s5, v254, 57
	s_add_u32 s54, s8, s4
	v_or3_b32 v4, v4, v7, v8
	v_add_lshl_u32 v2, v5, v2, 1
	s_addc_u32 s55, s9, s5
	s_add_i32 s71, s52, 0
	v_lshl_add_u32 v136, v4, 9, v2
	s_add_i32 m0, s71, 0x10000
	v_lshl_add_u32 v138, v6, 9, v2
	global_load_lds_dwordx4 v136, s[54:55]
	s_add_i32 m0, s71, 0x12000
	s_add_u32 s4, s54, 0x10000
	global_load_lds_dwordx4 v132, s[54:55]
	s_addc_u32 s5, s55, 0
	s_add_i32 m0, s71, 0x14000
	v_mov_b32_e32 v137, v99
	global_load_lds_dwordx4 v136, s[4:5]
	s_add_i32 m0, s71, 0x16000
	v_mov_b32_e32 v133, v99
	global_load_lds_dwordx4 v132, s[4:5]
	v_readlane_b32 s4, v254, 54
	v_readlane_b32 s5, v254, 55
	s_add_u32 s56, s6, s4
	s_addc_u32 s57, s7, s5
	s_add_i32 s72, s71, 0x2000
	s_mov_b32 m0, s71
	s_add_u32 s4, s56, 0x10000
	global_load_lds_dwordx4 v138, s[56:57]
	s_mov_b32 m0, s72
	s_addc_u32 s5, s57, 0
	s_add_i32 s73, s71, 0x4000
	global_load_lds_dwordx4 v134, s[56:57]
	s_mov_b32 m0, s73
	s_add_i32 s74, s71, 0x6000
	global_load_lds_dwordx4 v138, s[4:5]
	s_mov_b32 m0, s74
	v_mov_b32_e32 v139, v99
	global_load_lds_dwordx4 v134, s[4:5]
	v_mov_b32_e32 v135, v99
	s_cmp_eq_u32 s11, 1
	v_lshl_add_u64 v[8:9], s[54:55], 0, v[136:137]
	v_lshl_add_u64 v[6:7], s[54:55], 0, v[132:133]
	v_lshl_add_u64 v[2:3], s[56:57], 0, v[138:139]
	s_cselect_b64 s[4:5], -1, 0
	s_cmp_lg_u32 s11, 1
	v_lshl_add_u64 v[4:5], s[56:57], 0, v[134:135]
	s_cbranch_scc1 .LBB0_474
	s_barrier
